# position-DFT gemm_tile: second half-workgroup reads the A (DFT matrix) fragments from the first half's LDS image instead of staging its own copy (4 instead of 8 LDS-DMA pieces per step)
# speedup vs baseline: 1.0104x; 1.0021x over previous
; DI void phase_mix(KP p, int l, char* lds) {
;     ...
;       if (isl) { b = 2 * xcd + (i2 >> 5); mt = (i2 >> 1) & 15; nt = i2 & 1; K = 2048; Ap = DL + (size_t)mt * 128 * 2048; Bp = FTF + ((size_t)b * 256 + nt * 128) * 2048; sc = 0.00276213586f; rbase = (size_t)b * T + mt * 128; }
;       else { b = 2 * xcd + (i2 >> 2); mt = (i2 >> 1) & 1; nt = i2 & 1; K = 512; Ap = DC + (size_t)mt * 128 * 512; Bp = FTC + ((size_t)b * 256 + nt * 128) * 512; sc = 0.0078125f; rbase = (size_t)b * T + SEQ + mt * 128; }
;       bf16_t* yo = YD + rbase * 256 + nt * 128;
;       gemm_tile(Ap, K, Bp, K, K, lds, [&](int m, int n, f32x4 v) {
.LBB0_168:
	v_add_u32_e32 v160, v98, v96
	v_add_u32_e32 v192, v97, v96
	v_add_u32_e32 v161, v98, v99
	v_add_u32_e32 v193, v97, v99
	v_add_u32_e32 v190, v98, v100
	v_add_u32_e32 v194, v97, v100
	v_add_u32_e32 v191, v98, v101
	v_add_u32_e32 v195, v97, v101
	v_readfirstlane_b32 s74, v196
	s_lshr_b32 s74, s74, 8
	s_mul_i32 s75, s74, 0x11000
	s_nop 0
	v_subrev_u32_e32 v192, s75, v192
	v_subrev_u32_e32 v193, s75, v193
	v_subrev_u32_e32 v194, s75, v194
	v_subrev_u32_e32 v195, s75, v195
	ds_read_b128 v[128:131], v160 offset:16384
	ds_read_b128 v[132:135], v160 offset:20480
	ds_read_b128 v[136:139], v192 offset:0
	ds_read_b128 v[140:143], v192 offset:4096
	ds_read_b128 v[144:147], v161 offset:16384
	ds_read_b128 v[148:151], v161 offset:20480
	ds_read_b128 v[152:155], v193 offset:0
	ds_read_b128 v[156:159], v193 offset:4096
	ds_read_b128 v[216:219], v190 offset:16384
	ds_read_b128 v[220:223], v190 offset:20480
	ds_read_b128 v[224:227], v194 offset:0
	ds_read_b128 v[228:231], v194 offset:4096
	ds_read_b128 v[232:235], v191 offset:16384
	ds_read_b128 v[236:239], v191 offset:20480
	ds_read_b128 v[240:243], v195 offset:0
	ds_read_b128 v[244:247], v195 offset:4096
	s_waitcnt lgkmcnt(0)
	s_barrier
	s_cmp_lt_u32 s35, s5
	s_cbranch_scc0 .Ldl_s0_nodma
	s_cmp_lg_u32 s74, 0
	s_cbranch_scc1 .Ldl_skipA0
	v_add_u32_e32 v250, 0x0, v86
	v_lshl_add_u64 v[248:249], v[80:81], 0, v[0:1]
	v_readfirstlane_b32 s48, v250
	v_lshl_add_u64 v[248:249], v[248:249], 0, s[22:23]
	s_mov_b32 m0, s48
	s_nop 0
	global_load_lds_dwordx4 v[248:249], off
.Ldl_skipA0:
	v_mfma_f32_32x32x16_bf16 v[50:65], v[128:131], v[136:139], v[50:65]
	v_mfma_f32_32x32x16_bf16 v[34:49], v[132:135], v[136:139], v[34:49]
	v_add_u32_e32 v250, 0x4000, v86
	v_lshl_add_u64 v[248:249], v[72:73], 0, v[0:1]
	v_readfirstlane_b32 s48, v250
	v_lshl_add_u64 v[248:249], v[248:249], 0, s[22:23]
	s_mov_b32 m0, s48
	s_nop 0
	global_load_lds_dwordx4 v[248:249], off
	v_mfma_f32_32x32x16_bf16 v[18:33], v[128:131], v[140:143], v[18:33]
	v_mfma_f32_32x32x16_bf16 v[2:17], v[132:135], v[140:143], v[2:17]
	s_cmp_lg_u32 s74, 0
	s_cbranch_scc1 .Ldl_skipA1
	v_add_u32_e32 v250, 0x1000, v86
	v_lshl_add_u64 v[248:249], v[78:79], 0, v[0:1]
	v_readfirstlane_b32 s48, v250
	v_lshl_add_u64 v[248:249], v[248:249], 0, s[22:23]
	s_mov_b32 m0, s48
	s_nop 0
	global_load_lds_dwordx4 v[248:249], off
.Ldl_skipA1:
	v_mfma_f32_32x32x16_bf16 v[50:65], v[144:147], v[152:155], v[50:65]
	v_mfma_f32_32x32x16_bf16 v[34:49], v[148:151], v[152:155], v[34:49]
	v_add_u32_e32 v250, 0x5000, v86
	v_lshl_add_u64 v[248:249], v[70:71], 0, v[0:1]
	v_readfirstlane_b32 s48, v250
	v_lshl_add_u64 v[248:249], v[248:249], 0, s[22:23]
	s_mov_b32 m0, s48
	s_nop 0
	global_load_lds_dwordx4 v[248:249], off
	v_mfma_f32_32x32x16_bf16 v[18:33], v[144:147], v[156:159], v[18:33]
	v_mfma_f32_32x32x16_bf16 v[2:17], v[148:151], v[156:159], v[2:17]
	s_cmp_lg_u32 s74, 0
	s_cbranch_scc1 .Ldl_skipA2
	v_add_u32_e32 v250, 0x2000, v86
	v_lshl_add_u64 v[248:249], v[74:75], 0, v[0:1]
	v_readfirstlane_b32 s48, v250
	v_lshl_add_u64 v[248:249], v[248:249], 0, s[22:23]
	s_mov_b32 m0, s48
	s_nop 0
	global_load_lds_dwordx4 v[248:249], off
.Ldl_skipA2:
	v_mfma_f32_32x32x16_bf16 v[50:65], v[216:219], v[224:227], v[50:65]
	v_mfma_f32_32x32x16_bf16 v[34:49], v[220:223], v[224:227], v[34:49]
	v_add_u32_e32 v250, 0x6000, v86
	v_lshl_add_u64 v[248:249], v[66:67], 0, v[0:1]
	v_readfirstlane_b32 s48, v250
	v_lshl_add_u64 v[248:249], v[248:249], 0, s[22:23]
	s_mov_b32 m0, s48
	s_nop 0
	global_load_lds_dwordx4 v[248:249], off
	v_mfma_f32_32x32x16_bf16 v[18:33], v[216:219], v[228:231], v[18:33]
	v_mfma_f32_32x32x16_bf16 v[2:17], v[220:223], v[228:231], v[2:17]
	s_cmp_lg_u32 s74, 0
	s_cbranch_scc1 .Ldl_skipA3
	v_add_u32_e32 v250, 0x3000, v86
	v_lshl_add_u64 v[248:249], v[76:77], 0, v[0:1]
	v_readfirstlane_b32 s48, v250
	v_lshl_add_u64 v[248:249], v[248:249], 0, s[22:23]
	s_mov_b32 m0, s48
	s_nop 0
	global_load_lds_dwordx4 v[248:249], off
.Ldl_skipA3:
	v_mfma_f32_32x32x16_bf16 v[50:65], v[232:235], v[240:243], v[50:65]
	v_mfma_f32_32x32x16_bf16 v[34:49], v[236:239], v[240:243], v[34:49]
	v_add_u32_e32 v250, 0x7000, v86
	v_lshl_add_u64 v[248:249], v[68:69], 0, v[0:1]
	v_readfirstlane_b32 s48, v250
	v_lshl_add_u64 v[248:249], v[248:249], 0, s[22:23]
	s_mov_b32 m0, s48
	s_nop 0
	global_load_lds_dwordx4 v[248:249], off
	v_mfma_f32_32x32x16_bf16 v[18:33], v[232:235], v[244:247], v[18:33]
	v_mfma_f32_32x32x16_bf16 v[2:17], v[236:239], v[244:247], v[2:17]
	s_cmp_lg_u32 s74, 0
	s_cbranch_scc1 .Ldl_w4_0
	s_waitcnt vmcnt(8)
	s_branch .Ldl_wd_0
.Ldl_w4_0:
	s_waitcnt vmcnt(4)
.Ldl_wd_0:
	s_barrier
	s_branch .Ldl_s1

.Ldl_s1:
	ds_read_b128 v[128:131], v160 offset:49152
	ds_read_b128 v[132:135], v160 offset:53248
	ds_read_b128 v[136:139], v192 offset:32768
	ds_read_b128 v[140:143], v192 offset:36864
	ds_read_b128 v[144:147], v161 offset:49152
	ds_read_b128 v[148:151], v161 offset:53248
	ds_read_b128 v[152:155], v193 offset:32768
	ds_read_b128 v[156:159], v193 offset:36864
	ds_read_b128 v[216:219], v190 offset:49152
	ds_read_b128 v[220:223], v190 offset:53248
	ds_read_b128 v[224:227], v194 offset:32768
	ds_read_b128 v[228:231], v194 offset:36864
	ds_read_b128 v[232:235], v191 offset:49152
	ds_read_b128 v[236:239], v191 offset:53248
	ds_read_b128 v[240:243], v195 offset:32768
	ds_read_b128 v[244:247], v195 offset:36864
	s_waitcnt lgkmcnt(0)
	s_barrier
	s_add_i32 s48, s35, 1
	s_cmp_lt_u32 s48, s5
	s_cbranch_scc0 .Ldl_s1_nodma
	s_cmp_lg_u32 s74, 0
	s_cbranch_scc1 .Ldl_skipA4
	v_add_u32_e32 v250, 0x8000, v86
	v_lshl_add_u64 v[248:249], v[80:81], 0, v[0:1]
	v_readfirstlane_b32 s48, v250
	v_lshl_add_u64 v[248:249], v[248:249], 0, s[52:53]
	s_mov_b32 m0, s48
	s_nop 0
	global_load_lds_dwordx4 v[248:249], off
.Ldl_skipA4:
	v_mfma_f32_32x32x16_bf16 v[50:65], v[128:131], v[136:139], v[50:65]
	v_mfma_f32_32x32x16_bf16 v[34:49], v[132:135], v[136:139], v[34:49]
	v_add_u32_e32 v250, 0xc000, v86
	v_lshl_add_u64 v[248:249], v[72:73], 0, v[0:1]
	v_readfirstlane_b32 s48, v250
	v_lshl_add_u64 v[248:249], v[248:249], 0, s[52:53]
	s_mov_b32 m0, s48
	s_nop 0
	global_load_lds_dwordx4 v[248:249], off
	v_mfma_f32_32x32x16_bf16 v[18:33], v[128:131], v[140:143], v[18:33]
	v_mfma_f32_32x32x16_bf16 v[2:17], v[132:135], v[140:143], v[2:17]
	s_cmp_lg_u32 s74, 0
	s_cbranch_scc1 .Ldl_skipA5
	v_add_u32_e32 v250, 0x9000, v86
	v_lshl_add_u64 v[248:249], v[78:79], 0, v[0:1]
	v_readfirstlane_b32 s48, v250
	v_lshl_add_u64 v[248:249], v[248:249], 0, s[52:53]
	s_mov_b32 m0, s48
	s_nop 0
	global_load_lds_dwordx4 v[248:249], off
.Ldl_skipA5:
	v_mfma_f32_32x32x16_bf16 v[50:65], v[144:147], v[152:155], v[50:65]
	v_mfma_f32_32x32x16_bf16 v[34:49], v[148:151], v[152:155], v[34:49]
	v_add_u32_e32 v250, 0xd000, v86
	v_lshl_add_u64 v[248:249], v[70:71], 0, v[0:1]
	v_readfirstlane_b32 s48, v250
	v_lshl_add_u64 v[248:249], v[248:249], 0, s[52:53]
	s_mov_b32 m0, s48
	s_nop 0
	global_load_lds_dwordx4 v[248:249], off
	v_mfma_f32_32x32x16_bf16 v[18:33], v[144:147], v[156:159], v[18:33]
	v_mfma_f32_32x32x16_bf16 v[2:17], v[148:151], v[156:159], v[2:17]
	s_cmp_lg_u32 s74, 0
	s_cbranch_scc1 .Ldl_skipA6
	v_add_u32_e32 v250, 0xa000, v86
	v_lshl_add_u64 v[248:249], v[74:75], 0, v[0:1]
	v_readfirstlane_b32 s48, v250
	v_lshl_add_u64 v[248:249], v[248:249], 0, s[52:53]
	s_mov_b32 m0, s48
	s_nop 0
	global_load_lds_dwordx4 v[248:249], off
.Ldl_skipA6:
	v_mfma_f32_32x32x16_bf16 v[50:65], v[216:219], v[224:227], v[50:65]
	v_mfma_f32_32x32x16_bf16 v[34:49], v[220:223], v[224:227], v[34:49]
	v_add_u32_e32 v250, 0xe000, v86
	v_lshl_add_u64 v[248:249], v[66:67], 0, v[0:1]
	v_readfirstlane_b32 s48, v250
	v_lshl_add_u64 v[248:249], v[248:249], 0, s[52:53]
	s_mov_b32 m0, s48
	s_nop 0
	global_load_lds_dwordx4 v[248:249], off
	v_mfma_f32_32x32x16_bf16 v[18:33], v[216:219], v[228:231], v[18:33]
	v_mfma_f32_32x32x16_bf16 v[2:17], v[220:223], v[228:231], v[2:17]
	s_cmp_lg_u32 s74, 0
	s_cbranch_scc1 .Ldl_skipA7
	v_add_u32_e32 v250, 0xb000, v86
	v_lshl_add_u64 v[248:249], v[76:77], 0, v[0:1]
	v_readfirstlane_b32 s48, v250
	v_lshl_add_u64 v[248:249], v[248:249], 0, s[52:53]
	s_mov_b32 m0, s48
	s_nop 0
	global_load_lds_dwordx4 v[248:249], off
.Ldl_skipA7:
	v_mfma_f32_32x32x16_bf16 v[50:65], v[232:235], v[240:243], v[50:65]
	v_mfma_f32_32x32x16_bf16 v[34:49], v[236:239], v[240:243], v[34:49]
	v_add_u32_e32 v250, 0xf000, v86
	v_lshl_add_u64 v[248:249], v[68:69], 0, v[0:1]
	v_readfirstlane_b32 s48, v250
	v_lshl_add_u64 v[248:249], v[248:249], 0, s[52:53]
	s_mov_b32 m0, s48
	s_nop 0
	global_load_lds_dwordx4 v[248:249], off
	v_mfma_f32_32x32x16_bf16 v[18:33], v[232:235], v[244:247], v[18:33]
	v_mfma_f32_32x32x16_bf16 v[2:17], v[236:239], v[244:247], v[2:17]
	s_cmp_lg_u32 s74, 0
	s_cbranch_scc1 .Ldl_w4_1
	s_waitcnt vmcnt(8)
	s_branch .Ldl_wd_1
